# HGRN2 pass1/pass3 unit loops: lower-bound load issued first at loop top, vmcnt(0) replaced by counted waits so the next unit's prefetch stays in flight
# speedup vs baseline: 1.0093x; 1.0012x over previous
; __device__ __forceinline__ float bf2f(unsigned h) { return __uint_as_float(h << 16); }
; __device__ __forceinline__ unsigned cvt2(float lo, float hi) { bf16v2_t r = __builtin_convertvector((f32x2){lo, hi}, bf16v2_t); return __builtin_bit_cast(unsigned, r); }
; __device__ __forceinline__ float sigm_(float x) { return __builtin_amdgcn_rcpf(1.0f + __expf(-x)); }
; __device__ __forceinline__ void hgrn_pass3_all(LAS unsigned char* lds, const unsigned char* R, const bf16_t* ST, bf16_t* O, const float* ng, const float* lbp, int u0, int ustep, int tid) {
;     ...
;     u32x4 vw[2]; vw[0] = vwn[0]; vw[1] = vwn[1];
;     u32x2 ggv[4]; f32x4 g4v[4];
; #pragma unroll
;     for (int j = 0; j < 4; ++j) { const int v0 = 16 * (4 * vh + j) + 4 * fq; ggv[j] = *(const u32x2*)(GB + (r0 + 16 * tt + fr) * AW + h * 128 + v0); g4v[j] = *(const f32x4*)(ng + h * 128 + v0); }
;     float qv[16], lf[16];
; #pragma unroll
;     for (int i = 0; i < 16; ++i) { qv[i] = qn[i]; lf[i] = zn[i]; }
;     ...
;     const float rinv = rsqrtf((red[16 * tt + fr] + red[64 + 16 * tt + fr]) * (1.f / 128.f) + EPS);
;     const size_t row = r0 + 16 * tt + fr;
; #pragma unroll
;     for (int j = 0; j < 4; ++j) { const int v0 = 16 * (4 * vh + j) + 4 * fq;
;         const f32x4 g4 = g4v[j]; const u32x2 gg = ggv[j];
;         const float s0 = bf2f(gg.x & 0xffff), s1 = bf2f(gg.x >> 16), s2 = bf2f(gg.y & 0xffff), s3 = bf2f(gg.y >> 16);
;         u32x2 o; o.x = cvt2(o4[j][0] * rinv * g4[0] * (s0 * sigm_(s0)), o4[j][1] * rinv * g4[1] * (s1 * sigm_(s1)));
;         o.y = cvt2(o4[j][2] * rinv * g4[2] * (s2 * sigm_(s2)), o4[j][3] * rinv * g4[3] * (s3 * sigm_(s3)));
;         *(u32x2*)(O + row * D + h * 128 + v0) = o; }
.LBB0_95:
	s_or_b64 exec, exec, s[14:15]
	s_waitcnt lgkmcnt(0)
	s_barrier
	s_waitcnt vmcnt(0)
	ds_read2st64_b32 v[36:37], v143 offset1:1
	s_mov_b32 s14, 0x800000
	v_lshlrev_b32_e32 v40, 16, v126
	v_and_b32_e32 v41, 0xffff0000, v126
	v_lshlrev_b64 v[38:39], 11, v[128:129]
	s_waitcnt lgkmcnt(0)
	v_add_f32_e32 v36, v36, v37
	v_fmamk_f32 v36, v36, 0x3c000000, v204
	v_cmp_gt_f32_e32 vcc, s14, v36
	v_mul_f32_e32 v37, 0x4b800000, v36
	v_readlane_b32 s14, v252, 33
	v_cndmask_b32_e32 v36, v36, v37, vcc
	v_rsq_f32_e32 v36, v36
	v_readlane_b32 s15, v252, 34
	v_mov_b64_e32 v[102:103], v[14:15]
	v_mov_b64_e32 v[98:99], v[18:19]
	v_mul_f32_e32 v37, 0x45800000, v36
	v_cndmask_b32_e32 v36, v36, v37, vcc
	v_mul_f32_e32 v37, 0xbfb8aa3b, v40
	v_exp_f32_e32 v37, v37
	v_lshl_add_u64 v[38:39], s[14:15], 0, v[38:39]
	v_lshl_add_u64 v[38:39], v[38:39], 0, s[36:37]
	v_readlane_b32 s14, v254, 34
	v_add_f32_e32 v37, 1.0, v37
	v_rcp_f32_e32 v42, v37
	v_pk_mul_f32 v[44:45], v[80:81], v[36:37] op_sel_hi:[1,0]
	v_mul_f32_e32 v37, 0xbfb8aa3b, v41
	v_exp_f32_e32 v37, v37
	v_pk_mul_f32 v[28:29], v[28:29], v[44:45]
	s_add_i32 s66, s66, s14
	v_readlane_b32 s14, v254, 47
	v_add_f32_e32 v37, 1.0, v37
	v_rcp_f32_e32 v43, v37
	v_readlane_b32 s15, v254, 48
	s_andn2_b64 vcc, exec, s[60:61]
	v_mov_b32_e32 v221, v179
	v_pk_mul_f32 v[40:41], v[42:43], v[40:41]
	v_lshl_add_u64 v[116:117], v[116:117], 0, s[14:15]
	v_pk_mul_f32 v[28:29], v[40:41], v[28:29]
	v_mov_b32_e32 v220, v181
	v_cvt_pk_bf16_f32 v40, v28, v29
	v_lshlrev_b32_e32 v28, 16, v127
	v_mul_f32_e32 v37, 0xbfb8aa3b, v28
	v_exp_f32_e32 v37, v37
	v_and_b32_e32 v29, 0xffff0000, v127
	v_mov_b32_e32 v219, v182
	v_mov_b32_e32 v218, v183
	v_add_f32_e32 v37, 1.0, v37
	v_rcp_f32_e32 v42, v37
	v_pk_mul_f32 v[44:45], v[82:83], v[36:37] op_sel_hi:[1,0]
	v_mul_f32_e32 v37, 0xbfb8aa3b, v29
	v_exp_f32_e32 v37, v37
	v_pk_mul_f32 v[30:31], v[30:31], v[44:45]
	v_mov_b32_e32 v217, v184
	v_mov_b32_e32 v216, v186
	v_add_f32_e32 v37, 1.0, v37
	v_rcp_f32_e32 v43, v37
	v_mov_b32_e32 v215, v188
	v_mov_b32_e32 v214, v189
	v_mov_b32_e32 v213, v190
	v_pk_mul_f32 v[28:29], v[42:43], v[28:29]
	v_mov_b32_e32 v212, v191
	v_pk_mul_f32 v[28:29], v[28:29], v[30:31]
	v_lshlrev_b32_e32 v30, 16, v124
	v_mul_f32_e32 v37, 0xbfb8aa3b, v30
	v_exp_f32_e32 v37, v37
	v_cvt_pk_bf16_f32 v41, v28, v29
	v_lshl_add_u64 v[28:29], v[110:111], 1, v[38:39]
	v_and_b32_e32 v31, 0xffff0000, v124
	v_add_f32_e32 v37, 1.0, v37
	global_store_dwordx2 v[28:29], v[40:41], off
	v_rcp_f32_e32 v38, v37
	v_pk_mul_f32 v[40:41], v[64:65], v[36:37] op_sel_hi:[1,0]
	v_mul_f32_e32 v37, 0xbfb8aa3b, v31
	v_exp_f32_e32 v37, v37
	v_pk_mul_f32 v[24:25], v[24:25], v[40:41]
	v_mov_b32_e32 v211, v192
	v_mov_b32_e32 v210, v193
	v_add_f32_e32 v37, 1.0, v37
	v_rcp_f32_e32 v39, v37
	v_pk_mul_f32 v[40:41], v[66:67], v[36:37] op_sel_hi:[1,0]
	v_mov_b32_e32 v201, v194
	v_pk_mul_f32 v[26:27], v[26:27], v[40:41]
	v_pk_mul_f32 v[30:31], v[38:39], v[30:31]
	v_mov_b32_e32 v200, v195
	v_pk_mul_f32 v[24:25], v[30:31], v[24:25]
	v_lshlrev_b32_e32 v30, 16, v125
	v_cvt_pk_bf16_f32 v24, v24, v25
	v_mul_f32_e32 v25, 0xbfb8aa3b, v30
	v_exp_f32_e32 v25, v25
	v_and_b32_e32 v31, 0xffff0000, v125
	v_mov_b32_e32 v199, v196
	v_mov_b32_e32 v198, v197
	v_add_f32_e32 v25, 1.0, v25
	v_rcp_f32_e32 v38, v25
	v_mul_f32_e32 v25, 0xbfb8aa3b, v31
	v_exp_f32_e32 v25, v25
	v_mov_b32_e32 v227, v153
	v_mov_b32_e32 v226, v154
	v_mov_b32_e32 v230, v155
	v_add_f32_e32 v25, 1.0, v25
	v_rcp_f32_e32 v39, v25
	v_mov_b32_e32 v232, v156
	v_mov_b32_e32 v234, v157
	v_mov_b32_e32 v236, v158
	v_pk_mul_f32 v[30:31], v[38:39], v[30:31]
	v_mov_b32_e32 v225, v159
	v_pk_mul_f32 v[26:27], v[30:31], v[26:27]
	v_pk_mul_f32 v[30:31], v[48:49], v[36:37] op_sel_hi:[1,0]
	v_cvt_pk_bf16_f32 v25, v26, v27
	global_store_dwordx2 v[28:29], v[24:25], off offset:32
	v_lshlrev_b32_e32 v24, 16, v122
	v_and_b32_e32 v25, 0xffff0000, v122
	v_mul_f32_e32 v26, 0xbfb8aa3b, v24
	v_mul_f32_e32 v27, 0xbfb8aa3b, v25
	v_exp_f32_e32 v26, v26
	v_exp_f32_e32 v27, v27
	v_pk_mul_f32 v[20:21], v[20:21], v[30:31]
	v_pk_mul_f32 v[30:31], v[50:51], v[36:37] op_sel_hi:[1,0]
	v_add_f32_e32 v26, 1.0, v26
	v_add_f32_e32 v27, 1.0, v27
	v_rcp_f32_e32 v26, v26
	v_rcp_f32_e32 v27, v27
	v_pk_mul_f32 v[22:23], v[22:23], v[30:31]
	v_mov_b32_e32 v224, v160
	v_mov_b32_e32 v223, v161
	v_pk_mul_f32 v[24:25], v[26:27], v[24:25]
	v_mov_b32_e32 v222, v162
	v_pk_mul_f32 v[20:21], v[24:25], v[20:21]
	v_lshlrev_b32_e32 v24, 16, v123
	v_cvt_pk_bf16_f32 v20, v20, v21
	v_mul_f32_e32 v21, 0xbfb8aa3b, v24
	v_exp_f32_e32 v21, v21
	v_and_b32_e32 v25, 0xffff0000, v123
	v_mov_b32_e32 v135, v163
	v_mov_b32_e32 v134, v177
	v_add_f32_e32 v21, 1.0, v21
	v_rcp_f32_e32 v26, v21
	v_mul_f32_e32 v21, 0xbfb8aa3b, v25
	v_exp_f32_e32 v21, v21
	v_mov_b32_e32 v133, v178
	v_mov_b32_e32 v132, v180
	v_mov_b32_e32 v131, v185
	v_add_f32_e32 v21, 1.0, v21
	v_rcp_f32_e32 v27, v21
	v_mov_b32_e32 v130, v187
	v_mov_b64_e32 v[100:101], v[12:13]
	v_mov_b64_e32 v[96:97], v[16:17]
	v_pk_mul_f32 v[24:25], v[26:27], v[24:25]
	s_nop 0
	v_pk_mul_f32 v[22:23], v[24:25], v[22:23]
	v_pk_mul_f32 v[24:25], v[32:33], v[36:37] op_sel_hi:[1,0]
	v_cvt_pk_bf16_f32 v21, v22, v23
	global_store_dwordx2 v[28:29], v[20:21], off offset:64
	v_lshlrev_b32_e32 v20, 16, v120
	v_and_b32_e32 v21, 0xffff0000, v120
	v_mul_f32_e32 v22, 0xbfb8aa3b, v20
	v_mul_f32_e32 v23, 0xbfb8aa3b, v21
	v_exp_f32_e32 v22, v22
	v_exp_f32_e32 v23, v23
	v_pk_mul_f32 v[8:9], v[8:9], v[24:25]
	v_pk_mul_f32 v[24:25], v[34:35], v[36:37] op_sel_hi:[1,0]
	v_add_f32_e32 v22, 1.0, v22
	v_add_f32_e32 v23, 1.0, v23
	v_rcp_f32_e32 v22, v22
	v_rcp_f32_e32 v23, v23
	v_pk_mul_f32 v[10:11], v[10:11], v[24:25]
	v_pk_mul_f32 v[20:21], v[22:23], v[20:21]
	s_nop 0
	v_pk_mul_f32 v[8:9], v[20:21], v[8:9]
	v_lshlrev_b32_e32 v20, 16, v121
	v_cvt_pk_bf16_f32 v8, v8, v9
	v_mul_f32_e32 v9, 0xbfb8aa3b, v20
	v_exp_f32_e32 v9, v9
	v_and_b32_e32 v21, 0xffff0000, v121
	v_add_f32_e32 v9, 1.0, v9
	v_rcp_f32_e32 v22, v9
	v_mul_f32_e32 v9, 0xbfb8aa3b, v21
	v_exp_f32_e32 v9, v9
	s_nop 0
	v_add_f32_e32 v9, 1.0, v9
	v_rcp_f32_e32 v23, v9
	s_nop 0
	v_pk_mul_f32 v[20:21], v[22:23], v[20:21]
	s_nop 0
	v_pk_mul_f32 v[10:11], v[20:21], v[10:11]
	s_nop 0
	v_cvt_pk_bf16_f32 v9, v10, v11
	global_store_dwordx2 v[28:29], v[8:9], off offset:96
	s_cbranch_vccz .LBB0_115
; #define HG_LOADZ(dst, LFp, r0_) do { const float* lfp_ = (LFp) + (size_t)((r0_) + seg * 16) * AW + h * 128 + k; \
;     _Pragma("unroll") for (int i = 0; i < 16; ++i) (dst)[i] = lfp_[(size_t)i * AW]; } while (0)
; __device__ __forceinline__ void hgrn_pass3_all(LAS unsigned char* lds, const unsigned char* R, const bf16_t* ST, bf16_t* O, const float* ng, const float* lbp, int u0, int ustep, int tid) {
;     ...
;     for (int unit = u0; unit < 2048; unit += ustep) {
;     const int bh = unit >> 7, n = unit & 127, b = bh >> 2, h = bh & 3; const size_t r0 = (size_t)b * SEQ + n * 64;
;     bf16x8 aS[4][4];
;     { const bf16_t* sp = ST + (size_t)unit * 16384 + (size_t)(64 * vh + fr) * 128 + 8 * fq;
; #pragma unroll
;       for (int j = 0; j < 4; ++j)
; #pragma unroll
;         for (int ks = 0; ks < 4; ++ks) aS[j][ks] = *(const bf16x8*)(sp + (size_t)(16 * j) * 128 + 32 * ks); }
;     u32x4 vw[2]; vw[0] = vwn[0]; vw[1] = vwn[1];
;     u32x2 ggv[4]; f32x4 g4v[4];
; #pragma unroll
;     for (int j = 0; j < 4; ++j) { const int v0 = 16 * (4 * vh + j) + 4 * fq; ggv[j] = *(const u32x2*)(GB + (r0 + 16 * tt + fr) * AW + h * 128 + v0); g4v[j] = *(const f32x4*)(ng + h * 128 + v0); }
;     float qv[16], lf[16];
; #pragma unroll
;     for (int i = 0; i < 16; ++i) { qv[i] = qn[i]; lf[i] = zn[i]; }
;     __syncthreads();
;     { const int un = unit + ustep; if (un < 2048) { const int bh2 = un >> 7, n2 = un & 127, b2 = bh2 >> 2, h2 = bh2 & 3; const size_t r2 = (size_t)b2 * SEQ + n2 * 64;
;         { const int h = h2; HG_LOADZ(zn, LF, r2); HG_LOADZ(qn, Q, r2); } load_v(vwn, V + r2 * AW + h2 * 128, tid); } }
.LBB0_96:
	s_and_b32 vcc_lo, s67, 0x180
	v_or_b32_e32 v228, vcc_lo, v2
	v_lshlrev_b32_e32 v228, 2, v228
	global_load_dword v228, v228, s[2:3]
	s_movk_i32 s14, 0x1000
	s_ashr_i32 s16, s67, 9
	v_add_co_u32_e32 v8, vcc, s14, v116
	s_ashr_i32 s17, s16, 31
	s_nop 0
	v_addc_co_u32_e32 v9, vcc, 0, v117, vcc
	s_movk_i32 s14, 0x2000
	s_and_b32 s15, s66, 0x1fc0
	v_add_co_u32_e32 v10, vcc, s14, v116
	s_lshl_b64 s[16:17], s[16:17], 13
	s_nop 0
	v_addc_co_u32_e32 v11, vcc, 0, v117, vcc
	s_movk_i32 s14, 0x3000
	s_or_b32 s15, s16, s15
	global_load_dwordx4 v[88:91], v[116:117], off offset:64
	global_load_dwordx4 v[84:87], v[116:117], off offset:128
	global_load_dwordx4 v[80:83], v[116:117], off offset:192
	global_load_dwordx4 v[64:67], v[8:9], off offset:64
	global_load_dwordx4 v[68:71], v[8:9], off offset:128
	global_load_dwordx4 v[72:75], v[10:11], off offset:-4096
	global_load_dwordx4 v[52:55], v[10:11], off
	global_load_dwordx4 v[56:59], v[10:11], off offset:64
	global_load_dwordx4 v[60:63], v[10:11], off offset:128
	global_load_dwordx4 v[92:95], v[116:117], off
	global_load_dwordx4 v[48:51], v[10:11], off offset:192
	v_add_co_u32_e32 v10, vcc, s14, v116
	v_mov_b32_e32 v129, s17
	v_or_b32_e32 v128, s15, v112
	v_addc_co_u32_e32 v11, vcc, 0, v117, vcc
	global_load_dwordx4 v[76:79], v[8:9], off offset:192
	global_load_dwordx4 v[44:47], v[10:11], off
	global_load_dwordx4 v[40:43], v[10:11], off offset:64
	global_load_dwordx4 v[36:39], v[10:11], off offset:128
	global_load_dwordx4 v[32:35], v[10:11], off offset:192
	s_and_b32 s14, s67, 0x180
	v_lshlrev_b64 v[8:9], 10, v[128:129]
	v_lshl_add_u64 v[8:9], s[28:29], 0, v[8:9]
	s_lshl_b32 s36, s14, 1
	v_lshl_add_u64 v[8:9], v[8:9], 0, s[36:37]
	s_lshl_b32 s16, s14, 2
	s_mov_b32 s17, s37
	v_lshl_add_u64 v[8:9], v[110:111], 1, v[8:9]
	v_lshl_add_u64 v[10:11], v[114:115], 0, s[16:17]
	global_load_dwordx4 v[28:31], v[10:11], off
	global_load_dwordx4 v[24:27], v[10:11], off offset:64
	global_load_dwordx2 v[126:127], v[8:9], off
	global_load_dwordx2 v[124:125], v[8:9], off offset:32
	global_load_dwordx2 v[122:123], v[8:9], off offset:64
	global_load_dwordx2 v[120:121], v[8:9], off offset:96
	global_load_dwordx4 v[20:23], v[10:11], off offset:128
	s_nop 0
	global_load_dwordx4 v[8:11], v[10:11], off offset:192
	s_add_i32 s67, s67, s74
	s_cmpk_gt_i32 s67, 0x7ff
	s_cselect_b64 s[60:61], -1, 0
	s_and_b64 vcc, exec, s[60:61]
	s_barrier
	s_cbranch_vccnz .Lp3_last
	s_ashr_i32 s16, s67, 9
	s_ashr_i32 s17, s16, 31
	s_lshl_b64 s[40:41], s[16:17], 13
	v_readlane_b32 s16, v254, 34
	s_add_i32 s16, s16, s66
	s_and_b32 s16, s16, 0x1fc0
	s_or_b32 s40, s40, s16
	v_lshl_add_u64 v[12:13], s[40:41], 0, v[104:105]
	s_and_b32 s15, s67, 0x180
	v_lshlrev_b64 v[12:13], 11, v[12:13]
	v_lshl_add_u64 v[14:15], s[24:25], 0, v[12:13]
	s_lshl_b32 s54, s15, 2
	s_mov_b32 s55, s37
	v_lshl_add_u64 v[14:15], v[14:15], 0, s[54:55]
	v_lshl_add_u64 v[14:15], v[14:15], 0, v[0:1]
	s_movk_i32 s16, 0x1000
	v_add_co_u32_e32 v16, vcc, s16, v14
	s_movk_i32 s17, 0x2000
	s_nop 0
	v_addc_co_u32_e32 v17, vcc, 0, v15, vcc
	v_add_co_u32_e32 v18, vcc, s17, v14
	s_movk_i32 s18, 0x3000
	s_nop 0
	v_addc_co_u32_e32 v19, vcc, 0, v15, vcc
	global_load_dword v153, v[14:15], off
	global_load_dword v154, v[14:15], off offset:2048
	global_load_dword v155, v[18:19], off offset:-4096
	global_load_dword v156, v[16:17], off offset:2048
	global_load_dword v157, v[18:19], off
	global_load_dword v158, v[18:19], off offset:2048
	v_add_co_u32_e32 v16, vcc, s18, v14
	s_movk_i32 s19, 0x4000
	s_nop 0
	v_addc_co_u32_e32 v17, vcc, 0, v15, vcc
	v_add_co_u32_e32 v18, vcc, s19, v14
	s_movk_i32 s62, 0x5000
	s_nop 0
	v_addc_co_u32_e32 v19, vcc, 0, v15, vcc
	global_load_dword v159, v[18:19], off offset:-4096
	global_load_dword v160, v[16:17], off offset:2048
	global_load_dword v161, v[18:19], off
	global_load_dword v162, v[18:19], off offset:2048
	v_add_co_u32_e32 v16, vcc, s62, v14
	s_movk_i32 s63, 0x6000
	s_nop 0
	v_addc_co_u32_e32 v17, vcc, 0, v15, vcc
	v_readlane_b32 s76, v252, 30
	v_add_co_u32_e32 v18, vcc, s63, v14
	v_readlane_b32 s77, v252, 31
	s_nop 0
	v_addc_co_u32_e32 v19, vcc, 0, v15, vcc
	s_movk_i32 s70, 0x7000
	v_lshl_add_u64 v[12:13], s[76:77], 0, v[12:13]
	v_add_co_u32_e32 v14, vcc, s70, v14
	v_lshl_add_u64 v[12:13], v[12:13], 0, s[54:55]
	s_nop 0
	v_addc_co_u32_e32 v15, vcc, 0, v15, vcc
	v_lshl_add_u64 v[12:13], v[12:13], 0, v[0:1]
	global_load_dword v163, v[18:19], off offset:-4096
	global_load_dword v177, v[16:17], off offset:2048
	global_load_dword v178, v[18:19], off
	global_load_dword v180, v[18:19], off offset:2048
	global_load_dword v185, v[14:15], off
	global_load_dword v187, v[14:15], off offset:2048
	v_add_co_u32_e32 v14, vcc, s16, v12
	global_load_dword v179, v[12:13], off
	global_load_dword v181, v[12:13], off offset:2048
	v_addc_co_u32_e32 v15, vcc, 0, v13, vcc
	v_add_co_u32_e32 v16, vcc, s17, v12
	s_lshl_b64 s[16:17], s[40:41], 10
	s_nop 0
	v_addc_co_u32_e32 v17, vcc, 0, v13, vcc
	global_load_dword v182, v[16:17], off offset:-4096
	global_load_dword v183, v[14:15], off offset:2048
	global_load_dword v184, v[16:17], off
	global_load_dword v186, v[16:17], off offset:2048
	v_add_co_u32_e32 v14, vcc, s18, v12
	s_add_u32 s16, s23, s16
	s_nop 0
	v_addc_co_u32_e32 v15, vcc, 0, v13, vcc
	v_add_co_u32_e32 v16, vcc, s19, v12
	s_addc_u32 s17, s35, s17
	s_nop 0
	v_addc_co_u32_e32 v17, vcc, 0, v13, vcc
	global_load_dword v188, v[16:17], off offset:-4096
	global_load_dword v189, v[14:15], off offset:2048
	global_load_dword v190, v[16:17], off
	global_load_dword v191, v[16:17], off offset:2048
	v_add_co_u32_e32 v14, vcc, s62, v12
	s_lshl_b32 s15, s15, 1
	s_nop 0
	v_addc_co_u32_e32 v15, vcc, 0, v13, vcc
	v_add_co_u32_e32 v16, vcc, s63, v12
	s_add_u32 s16, s16, s15
	s_nop 0
	v_addc_co_u32_e32 v17, vcc, 0, v13, vcc
	v_add_co_u32_e32 v12, vcc, s70, v12
	s_addc_u32 s17, s17, 0
	v_mov_b32_e32 v119, v1
	global_load_dword v192, v[16:17], off offset:-4096
	global_load_dword v193, v[14:15], off offset:2048
	global_load_dword v194, v[16:17], off
	global_load_dword v195, v[16:17], off offset:2048
	v_addc_co_u32_e32 v13, vcc, 0, v13, vcc
	v_lshl_add_u64 v[16:17], s[16:17], 0, v[118:119]
	global_load_dword v196, v[12:13], off
	global_load_dword v197, v[12:13], off offset:2048
	v_lshl_add_u64 v[12:13], v[106:107], 1, v[16:17]
	v_lshl_add_u64 v[16:17], v[108:109], 1, v[16:17]
	global_load_dwordx4 v[12:15], v[12:13], off
	s_nop 0
	global_load_dwordx4 v[16:19], v[16:17], off
.LBB0_98:
	v_mul_f32_e32 v119, 0xbfb8aa3b, v227
	v_exp_f32_e32 v119, v119
	s_mov_b32 s14, 0x800000
	v_mul_f32_e32 v226, 0xbfb8aa3b, v226
	v_exp_f32_e32 v226, v226
	v_add_f32_e32 v119, 1.0, v119
	v_rcp_f32_e32 v119, v119
	s_mov_b32 s15, 0x3f317217
	v_add_f32_e32 v226, 1.0, v226
	v_rcp_f32_e32 v226, v226
	s_mov_b32 s16, 0x7f800000
	v_mul_f32_e32 v230, 0xbfb8aa3b, v230
	v_exp_f32_e32 v230, v230
	v_mul_f32_e32 v232, 0xbfb8aa3b, v232
	v_exp_f32_e32 v232, v232
	v_mul_f32_e32 v234, 0xbfb8aa3b, v234
	v_add_f32_e32 v230, 1.0, v230
	v_rcp_f32_e32 v230, v230
	v_add_f32_e32 v232, 1.0, v232
	v_rcp_f32_e32 v232, v232
	v_exp_f32_e32 v234, v234
	v_mul_f32_e32 v236, 0xbfb8aa3b, v236
	v_exp_f32_e32 v236, v236
	v_mul_f32_e32 v225, 0xbfb8aa3b, v225
	v_add_f32_e32 v234, 1.0, v234
	v_rcp_f32_e32 v234, v234
	v_add_f32_e32 v236, 1.0, v236
	v_rcp_f32_e32 v236, v236
	v_exp_f32_e32 v225, v225
	v_mul_f32_e32 v224, 0xbfb8aa3b, v224
	v_exp_f32_e32 v224, v224
	v_mul_f32_e32 v223, 0xbfb8aa3b, v223
	v_add_f32_e32 v225, 1.0, v225
	v_rcp_f32_e32 v225, v225
	v_add_f32_e32 v224, 1.0, v224
	v_rcp_f32_e32 v224, v224
	v_exp_f32_e32 v223, v223
	v_mul_f32_e32 v222, 0xbfb8aa3b, v222
	v_exp_f32_e32 v222, v222
	v_mul_f32_e32 v135, 0xbfb8aa3b, v135
	v_add_f32_e32 v223, 1.0, v223
	v_rcp_f32_e32 v223, v223
	v_add_f32_e32 v222, 1.0, v222
	v_rcp_f32_e32 v222, v222
	v_exp_f32_e32 v135, v135
	v_mul_f32_e32 v134, 0xbfb8aa3b, v134
	v_exp_f32_e32 v134, v134
	v_mul_f32_e32 v133, 0xbfb8aa3b, v133
	v_add_f32_e32 v135, 1.0, v135
	v_rcp_f32_e32 v135, v135
	v_add_f32_e32 v134, 1.0, v134
	v_rcp_f32_e32 v134, v134
	v_exp_f32_e32 v133, v133
	v_mul_f32_e32 v132, 0xbfb8aa3b, v132
	v_exp_f32_e32 v132, v132
	v_mul_f32_e32 v131, 0xbfb8aa3b, v131
	v_add_f32_e32 v133, 1.0, v133
	v_rcp_f32_e32 v133, v133
	v_add_f32_e32 v132, 1.0, v132
	v_rcp_f32_e32 v132, v132
	v_exp_f32_e32 v131, v131
	v_mul_f32_e32 v130, 0xbfb8aa3b, v130
	v_exp_f32_e32 v130, v130
	v_add_f32_e32 v131, 1.0, v131
	v_rcp_f32_e32 v131, v131
	v_add_f32_e32 v130, 1.0, v130
	v_rcp_f32_e32 v130, v130
	s_waitcnt vmcnt(58)
	v_sub_f32_e32 v229, 1.0, v228
	v_fma_f32 v119, v119, v229, v228
	v_max_f32_e32 v119, 0x1e3ce508, v119
	v_cmp_gt_f32_e32 vcc, s14, v119
	v_fma_f32 v226, v226, v229, v228
	v_max_f32_e32 v226, 0x1e3ce508, v226
	v_cndmask_b32_e64 v227, 0, 32, vcc
	v_ldexp_f32 v227, v119, v227
	v_log_f32_e32 v227, v227
	v_fma_f32 v230, v230, v229, v228
	v_max_f32_e32 v230, 0x1e3ce508, v230
	v_fma_f32 v232, v232, v229, v228
	v_mul_f32_e32 v231, 0x3f317217, v227
	v_fma_f32 v231, v227, s15, -v231
	v_fmac_f32_e32 v231, 0x3377d1cf, v227
	v_fmac_f32_e32 v231, 0x3f317217, v227
	v_cmp_lt_f32_e64 s[54:55], |v227|, s16
	v_max_f32_e32 v232, 0x1e3ce508, v232
	v_fma_f32 v234, v234, v229, v228
	v_cndmask_b32_e64 v227, v227, v231, s[54:55]
	v_cndmask_b32_e32 v231, 0, v209, vcc
	v_cmp_gt_f32_e32 vcc, s14, v226
	v_sub_f32_e32 v227, v227, v231
	v_max_f32_e32 v234, 0x1e3ce508, v234
	v_cndmask_b32_e64 v231, 0, 32, vcc
	v_ldexp_f32 v231, v226, v231
	v_log_f32_e32 v231, v231
	v_fma_f32 v236, v236, v229, v228
	v_max_f32_e32 v236, 0x1e3ce508, v236
	v_fma_f32 v225, v225, v229, v228
	v_mul_f32_e32 v233, 0x3f317217, v231
	v_fma_f32 v233, v231, s15, -v233
	v_fmac_f32_e32 v233, 0x3377d1cf, v231
	v_fmac_f32_e32 v233, 0x3f317217, v231
	v_cmp_lt_f32_e64 s[54:55], |v231|, s16
	v_max_f32_e32 v225, 0x1e3ce508, v225
	v_fma_f32 v224, v224, v229, v228
	v_cndmask_b32_e64 v231, v231, v233, s[54:55]
	v_cndmask_b32_e32 v233, 0, v209, vcc
	v_cmp_gt_f32_e32 vcc, s14, v230
	v_sub_f32_e32 v231, v231, v233
	v_max_f32_e32 v224, 0x1e3ce508, v224
	v_cndmask_b32_e64 v233, 0, 32, vcc
	v_ldexp_f32 v233, v230, v233
	v_log_f32_e32 v233, v233
	v_fma_f32 v223, v223, v229, v228
	v_max_f32_e32 v223, 0x1e3ce508, v223
	v_fma_f32 v222, v222, v229, v228
	v_mul_f32_e32 v235, 0x3f317217, v233
	v_fma_f32 v235, v233, s15, -v235
	v_fmac_f32_e32 v235, 0x3377d1cf, v233
	v_fmac_f32_e32 v235, 0x3f317217, v233
	v_cmp_lt_f32_e64 s[54:55], |v233|, s16
	v_max_f32_e32 v222, 0x1e3ce508, v222
	v_fma_f32 v135, v135, v229, v228
	v_cndmask_b32_e64 v233, v233, v235, s[54:55]
	v_cndmask_b32_e32 v235, 0, v209, vcc
	v_cmp_gt_f32_e32 vcc, s14, v232
	v_sub_f32_e32 v233, v233, v235
	v_fma_f32 v134, v134, v229, v228
	v_cndmask_b32_e64 v235, 0, 32, vcc
	v_ldexp_f32 v235, v232, v235
	v_log_f32_e32 v235, v235
	v_fma_f32 v133, v133, v229, v228
	v_max_f32_e32 v133, 0x1e3ce508, v133
	v_fma_f32 v132, v132, v229, v228
	v_mul_f32_e32 v237, 0x3f317217, v235
	v_fma_f32 v237, v235, s15, -v237
	v_fmac_f32_e32 v237, 0x3377d1cf, v235
	v_fmac_f32_e32 v237, 0x3f317217, v235
	v_cmp_lt_f32_e64 s[54:55], |v235|, s16
	v_fma_f32 v131, v131, v229, v228
	v_max_f32_e32 v131, 0x1e3ce508, v131
	v_cndmask_b32_e64 v235, v235, v237, s[54:55]
	v_cndmask_b32_e32 v237, 0, v209, vcc
	v_cmp_gt_f32_e32 vcc, s14, v234
	v_sub_f32_e32 v235, v235, v237
	v_fmac_f32_e32 v228, v130, v229
	v_cndmask_b32_e64 v237, 0, 32, vcc
	v_ldexp_f32 v237, v234, v237
	v_log_f32_e32 v237, v237
	v_max_f32_e32 v228, 0x1e3ce508, v228
	v_mul_f32_e32 v238, 0x3f317217, v237
	v_fma_f32 v238, v237, s15, -v238
	v_fmac_f32_e32 v238, 0x3377d1cf, v237
	v_fmac_f32_e32 v238, 0x3f317217, v237
	v_cmp_lt_f32_e64 s[54:55], |v237|, s16
	s_nop 1
	v_cndmask_b32_e64 v237, v237, v238, s[54:55]
	v_cndmask_b32_e32 v238, 0, v209, vcc
	v_cmp_gt_f32_e32 vcc, s14, v236
	v_sub_f32_e32 v237, v237, v238
	s_nop 0
	v_cndmask_b32_e64 v238, 0, 32, vcc
	v_ldexp_f32 v238, v236, v238
	v_log_f32_e32 v238, v238
	s_nop 0
	v_mul_f32_e32 v239, 0x3f317217, v238
	v_fma_f32 v239, v238, s15, -v239
	v_fmac_f32_e32 v239, 0x3377d1cf, v238
	v_fmac_f32_e32 v239, 0x3f317217, v238
	v_cmp_lt_f32_e64 s[54:55], |v238|, s16
	s_nop 1
	v_cndmask_b32_e64 v238, v238, v239, s[54:55]
	v_cndmask_b32_e32 v239, 0, v209, vcc
	v_cmp_gt_f32_e32 vcc, s14, v225
	v_sub_f32_e32 v238, v238, v239
	s_nop 0
	v_cndmask_b32_e64 v239, 0, 32, vcc
	v_ldexp_f32 v239, v225, v239
	v_log_f32_e32 v239, v239
	s_nop 0
	v_mul_f32_e32 v240, 0x3f317217, v239
	v_fma_f32 v240, v239, s15, -v240
	v_fmac_f32_e32 v240, 0x3377d1cf, v239
	v_fmac_f32_e32 v240, 0x3f317217, v239
	v_cmp_lt_f32_e64 s[54:55], |v239|, s16
	s_nop 1
	v_cndmask_b32_e64 v239, v239, v240, s[54:55]
	v_cndmask_b32_e32 v240, 0, v209, vcc
	v_cmp_gt_f32_e32 vcc, s14, v224
	v_sub_f32_e32 v239, v239, v240
	s_nop 0
	v_cndmask_b32_e64 v240, 0, 32, vcc
	v_ldexp_f32 v240, v224, v240
	v_log_f32_e32 v240, v240
	s_nop 0
	v_mul_f32_e32 v241, 0x3f317217, v240
	v_fma_f32 v241, v240, s15, -v241
	v_fmac_f32_e32 v241, 0x3377d1cf, v240
	v_fmac_f32_e32 v241, 0x3f317217, v240
	v_cmp_lt_f32_e64 s[54:55], |v240|, s16
	s_nop 1
	v_cndmask_b32_e64 v240, v240, v241, s[54:55]
	v_cndmask_b32_e32 v241, 0, v209, vcc
	v_cmp_gt_f32_e32 vcc, s14, v223
	v_sub_f32_e32 v240, v240, v241
	s_nop 0
	v_cndmask_b32_e64 v241, 0, 32, vcc
	v_ldexp_f32 v241, v223, v241
	v_log_f32_e32 v241, v241
	s_nop 0
	v_mul_f32_e32 v242, 0x3f317217, v241
	v_fma_f32 v242, v241, s15, -v242
	v_fmac_f32_e32 v242, 0x3377d1cf, v241
	v_fmac_f32_e32 v242, 0x3f317217, v241
	v_cmp_lt_f32_e64 s[54:55], |v241|, s16
	s_nop 1
	v_cndmask_b32_e64 v241, v241, v242, s[54:55]
	v_cndmask_b32_e32 v242, 0, v209, vcc
	v_cmp_gt_f32_e32 vcc, s14, v222
	v_sub_f32_e32 v241, v241, v242
	s_nop 0
	v_cndmask_b32_e64 v242, 0, 32, vcc
	v_ldexp_f32 v242, v222, v242
	v_log_f32_e32 v242, v242
	s_nop 0
	v_mul_f32_e32 v243, 0x3f317217, v242
	v_fma_f32 v243, v242, s15, -v243
	v_fmac_f32_e32 v243, 0x3377d1cf, v242
	v_fmac_f32_e32 v243, 0x3f317217, v242
	v_cmp_lt_f32_e64 s[54:55], |v242|, s16
	s_nop 1
	v_cndmask_b32_e64 v242, v242, v243, s[54:55]
	v_cndmask_b32_e32 v243, 0, v209, vcc
	v_sub_f32_e32 v248, v242, v243
	v_max_f32_e32 v242, 0x1e3ce508, v135
	v_cmp_gt_f32_e32 vcc, s14, v242
	s_nop 1
	v_cndmask_b32_e64 v135, 0, 32, vcc
	v_ldexp_f32 v135, v242, v135
	v_log_f32_e32 v135, v135
	s_nop 0
	v_mul_f32_e32 v243, 0x3f317217, v135
	v_fma_f32 v243, v135, s15, -v243
	v_fmac_f32_e32 v243, 0x3377d1cf, v135
	v_fmac_f32_e32 v243, 0x3f317217, v135
	v_cmp_lt_f32_e64 s[54:55], |v135|, s16
	s_nop 1
	v_cndmask_b32_e64 v135, v135, v243, s[54:55]
	v_cndmask_b32_e32 v243, 0, v209, vcc
	v_sub_f32_e32 v135, v135, v243
	v_max_f32_e32 v243, 0x1e3ce508, v134
	v_cmp_gt_f32_e32 vcc, s14, v243
	s_nop 1
	v_cndmask_b32_e64 v134, 0, 32, vcc
	v_ldexp_f32 v134, v243, v134
	v_log_f32_e32 v134, v134
	s_nop 0
	v_mul_f32_e32 v244, 0x3f317217, v134
	v_fma_f32 v244, v134, s15, -v244
	v_fmac_f32_e32 v244, 0x3377d1cf, v134
	v_fmac_f32_e32 v244, 0x3f317217, v134
	v_cmp_lt_f32_e64 s[54:55], |v134|, s16
	s_nop 1
	v_cndmask_b32_e64 v134, v134, v244, s[54:55]
	v_cndmask_b32_e32 v244, 0, v209, vcc
	v_cmp_gt_f32_e32 vcc, s14, v133
	v_sub_f32_e32 v134, v134, v244
	s_nop 0
	v_cndmask_b32_e64 v244, 0, 32, vcc
	v_ldexp_f32 v244, v133, v244
	v_log_f32_e32 v244, v244
	s_nop 0
	v_mul_f32_e32 v245, 0x3f317217, v244
	v_fma_f32 v245, v244, s15, -v245
	v_fmac_f32_e32 v245, 0x3377d1cf, v244
	v_fmac_f32_e32 v245, 0x3f317217, v244
	v_cmp_lt_f32_e64 s[54:55], |v244|, s16
	s_nop 1
	v_cndmask_b32_e64 v244, v244, v245, s[54:55]
	v_cndmask_b32_e32 v245, 0, v209, vcc
	v_sub_f32_e32 v250, v244, v245
	v_max_f32_e32 v244, 0x1e3ce508, v132
	v_cmp_gt_f32_e32 vcc, s14, v244
	s_nop 1
	v_cndmask_b32_e64 v132, 0, 32, vcc
	v_ldexp_f32 v132, v244, v132
	v_log_f32_e32 v132, v132
	s_nop 0
	v_mul_f32_e32 v245, 0x3f317217, v132
	v_fma_f32 v245, v132, s15, -v245
	v_fmac_f32_e32 v245, 0x3377d1cf, v132
	v_fmac_f32_e32 v245, 0x3f317217, v132
	v_cmp_lt_f32_e64 s[54:55], |v132|, s16
	s_nop 1
	v_cndmask_b32_e64 v132, v132, v245, s[54:55]
	v_cndmask_b32_e32 v245, 0, v209, vcc
	v_cmp_gt_f32_e32 vcc, s14, v131
	v_sub_f32_e32 v132, v132, v245
	s_nop 0
	v_cndmask_b32_e64 v245, 0, 32, vcc
	v_ldexp_f32 v245, v131, v245
	v_log_f32_e32 v245, v245
	s_nop 0
	v_mul_f32_e32 v246, 0x3f317217, v245
	v_fma_f32 v246, v245, s15, -v246
	v_fmac_f32_e32 v246, 0x3377d1cf, v245
	v_fmac_f32_e32 v246, 0x3f317217, v245
	v_cmp_lt_f32_e64 s[54:55], |v245|, s16
	s_nop 1
	v_cndmask_b32_e64 v245, v245, v246, s[54:55]
	v_cndmask_b32_e32 v246, 0, v209, vcc
	v_cmp_gt_f32_e32 vcc, s14, v228
	v_sub_f32_e32 v251, v245, v246
	s_nop 0
	v_cndmask_b32_e64 v130, 0, 32, vcc
	v_ldexp_f32 v130, v228, v130
	v_log_f32_e32 v130, v130
	s_nop 0
	v_mul_f32_e32 v229, 0x3f317217, v130
	v_fma_f32 v229, v130, s15, -v229
	v_fmac_f32_e32 v229, 0x3377d1cf, v130
	v_fmac_f32_e32 v229, 0x3f317217, v130
	v_cmp_lt_f32_e64 s[54:55], |v130|, s16
	s_nop 1
	v_cndmask_b32_e64 v130, v130, v229, s[54:55]
	v_cndmask_b32_e32 v229, 0, v209, vcc
	v_sub_f32_e32 v229, v130, v229
	v_add_f32_e32 v130, 0, v227
	v_add_f32_e32 v245, v231, v130
	v_add_f32_e32 v246, v233, v245
	v_add_f32_e32 v247, v235, v246
	v_add_f32_e32 v237, v237, v247
	v_add_f32_e32 v238, v238, v237
	v_add_f32_e32 v239, v239, v238
	v_add_f32_e32 v240, v240, v239
	v_add_f32_e32 v241, v241, v240
	v_add_f32_e32 v248, v248, v241
	v_add_f32_e32 v249, v135, v248
	v_add_f32_e32 v231, v134, v249
	v_add_f32_e32 v233, v250, v231
	v_add_f32_e32 v235, v132, v233
	v_add_f32_e32 v227, v251, v235
	v_add_f32_e32 v229, v229, v227
	ds_write_b32 v113, v229
	s_waitcnt lgkmcnt(0)
	s_barrier
	ds_read2st64_b32 v[134:135], v136 offset1:2
	v_mov_b32_e32 v132, 0
	s_and_saveexec_b64 s[40:41], s[6:7]
	s_cbranch_execz .LBB0_106
	ds_read_b32 v250, v136 offset:1024
	v_cmp_lt_i32_e32 vcc, 1, v3
	s_mov_b64 s[14:15], 0
	s_and_saveexec_b64 s[16:17], vcc
	s_xor_b64 s[54:55], exec, s[16:17]
	s_cbranch_execz .LBB0_108
	v_cmp_eq_u32_e32 vcc, 2, v3
	s_mov_b64 s[14:15], -1
	s_and_saveexec_b64 s[62:63], vcc
	s_cbranch_execz .LBB0_102
	s_waitcnt lgkmcnt(1)
	v_add_f32_e32 v132, v134, v135
	s_xor_b64 s[14:15], exec, -1

; #define LAS __attribute__((address_space(3)))
; #define MFMA16(a, b, c) __builtin_amdgcn_mfma_f32_16x16x32_bf16(a, b, c, 0, 0, 0)
; __device__ __forceinline__ unsigned cvt2(float lo, float hi) { bf16v2_t r = __builtin_convertvector((f32x2){lo, hi}, bf16v2_t); return __builtin_bit_cast(unsigned, r); }
; __device__ __forceinline__ void hgrn_pass3_all(LAS unsigned char* lds, const unsigned char* R, const bf16_t* ST, bf16_t* O, const float* ng, const float* lbp, int u0, int ustep, int tid) {
;     ...
;         u32x2 o; o.x = cvt2(acc[0], acc[1]); o.y = cvt2(acc[2], acc[3]);
;         *(LAS u32x2*)(pp + (16 * tt + fr) * KT_STRIDE + (16 * st + 4 * fq) * 2) = o; }
;     __syncthreads();
;     f32x4 o4[4];
;     { bf16x8 bP[2], bQ[4];
; #pragma unroll
;       for (int ks = 0; ks < 2; ++ks) bP[ks] = LDFRAG(pp, 16 * tt + fr, KT_STRIDE, 32 * ks + 8 * fq);
; #pragma unroll
;       for (int ks = 0; ks < 4; ++ks) bQ[ks] = LDFRAG(qs, 16 * tt + fr, QK_STRIDE, 32 * ks + 8 * fq);
; #pragma unroll
;       for (int j = 0; j < 4; ++j) { f32x4 acc = (f32x4){0.f, 0.f, 0.f, 0.f};
; #pragma unroll
;         for (int ks = 0; ks < 2; ++ks) acc = MFMA16(LDFRAG(vt, 16 * (4 * vh + j) + fr, KT_STRIDE, 32 * ks + 8 * fq), bP[ks], acc);
; #pragma unroll
;         for (int ks = 0; ks < 4; ++ks) acc = MFMA16(aS[j][ks], bQ[ks], acc);
;         o4[j] = acc; } }
;     float ss = 0.f;
; #pragma unroll
;     for (int j = 0; j < 4; ++j) ss += (o4[j][0] * o4[j][0] + o4[j][1] * o4[j][1]) + (o4[j][2] * o4[j][2] + o4[j][3] * o4[j][3]);
;     ss += __shfl_xor(ss, 16); ss += __shfl_xor(ss, 32);
;     if (fq == 0) red[vh * 64 + 16 * tt + fr] = ss;
.LBB0_113:
	v_cvt_pk_bf16_f32 v96, v96, v97
	v_cvt_pk_bf16_f32 v97, v98, v99
	v_add_u32_e32 v98, s65, v138
	ds_write_b64 v98, v[96:97]
	s_waitcnt lgkmcnt(0)
	s_barrier
	ds_read_b128 v[96:99], v151
	v_add_u32_e32 v119, v137, v139
	ds_read_b128 v[100:103], v119
	ds_read_b128 v[130:133], v151 offset:64
	ds_read_b128 v[198:201], v119 offset:64
	ds_read_b128 v[210:213], v150
	s_waitcnt lgkmcnt(3)
	v_mfma_f32_16x16x32_bf16 v[96:99], v[96:99], v[100:103], 0
	s_waitcnt lgkmcnt(1)
	v_mfma_f32_16x16x32_bf16 v[96:99], v[130:133], v[198:201], v[96:99]
	ds_read_b128 v[130:133], v151 offset:2304
	s_waitcnt lgkmcnt(1)
	s_waitcnt vmcnt(34)
	v_mfma_f32_16x16x32_bf16 v[92:95], v[92:95], v[210:213], v[96:99]
	s_nop 4
	ds_read_b128 v[96:99], v150 offset:64
	s_waitcnt lgkmcnt(0)
	v_mfma_f32_16x16x32_bf16 v[88:91], v[88:91], v[96:99], v[92:95]
	s_nop 2
	ds_read_b128 v[92:95], v150 offset:128
	s_waitcnt lgkmcnt(0)
	v_mfma_f32_16x16x32_bf16 v[84:87], v[84:87], v[92:95], v[88:91]
	s_nop 2
	ds_read_b128 v[88:91], v150 offset:192
	s_waitcnt lgkmcnt(0)
	v_mfma_f32_16x16x32_bf16 v[80:83], v[80:83], v[88:91], v[84:87]
	s_nop 2
	ds_read_b128 v[84:87], v151 offset:2368
	v_mfma_f32_16x16x32_bf16 v[130:133], v[130:133], v[100:103], 0
	s_waitcnt lgkmcnt(0)
	v_mfma_f32_16x16x32_bf16 v[84:87], v[84:87], v[198:201], v[130:133]
	v_mfma_f32_16x16x32_bf16 v[72:75], v[72:75], v[210:213], v[84:87]
	v_mfma_f32_16x16x32_bf16 v[64:67], v[64:67], v[96:99], v[72:75]
	v_mfma_f32_16x16x32_bf16 v[64:67], v[68:71], v[92:95], v[64:67]
	ds_read_b128 v[68:71], v151 offset:4608
	s_nop 4
	ds_read_b128 v[72:75], v151 offset:4672
	s_waitcnt lgkmcnt(1)
	v_mfma_f32_16x16x32_bf16 v[68:71], v[68:71], v[100:103], 0
	s_waitcnt lgkmcnt(0)
	v_mfma_f32_16x16x32_bf16 v[68:71], v[72:75], v[198:201], v[68:71]
	v_mfma_f32_16x16x32_bf16 v[52:55], v[52:55], v[210:213], v[68:71]
	v_mfma_f32_16x16x32_bf16 v[52:55], v[56:59], v[96:99], v[52:55]
	ds_read_b128 v[56:59], v151 offset:6912
	v_mfma_f32_16x16x32_bf16 v[52:55], v[60:63], v[92:95], v[52:55]
	v_mul_f32_e32 v60, v81, v81
	v_mul_f32_e32 v61, v83, v83
	v_fmac_f32_e32 v60, v80, v80
	v_mfma_f32_16x16x32_bf16 v[48:51], v[48:51], v[88:91], v[52:55]
	v_fmac_f32_e32 v61, v82, v82
	v_add_f32_e32 v60, v60, v61
	s_nop 1
	ds_read_b128 v[52:55], v151 offset:6976
	s_waitcnt lgkmcnt(1)
	v_mfma_f32_16x16x32_bf16 v[56:59], v[56:59], v[100:103], 0
	s_waitcnt lgkmcnt(0)
	v_mfma_f32_16x16x32_bf16 v[52:55], v[52:55], v[198:201], v[56:59]
	v_mfma_f32_16x16x32_bf16 v[44:47], v[44:47], v[210:213], v[52:55]
	v_mfma_f32_16x16x32_bf16 v[40:43], v[40:43], v[96:99], v[44:47]
	v_mfma_f32_16x16x32_bf16 v[36:39], v[36:39], v[92:95], v[40:43]
	s_nop 5
	v_mul_f32_e32 v44, v49, v49
	v_mul_f32_e32 v45, v51, v51
	v_fmac_f32_e32 v44, v48, v48
	v_mfma_f32_16x16x32_bf16 v[64:67], v[76:79], v[88:91], v[64:67]
	v_fmac_f32_e32 v45, v50, v50
	v_add_f32_e32 v40, v44, v45
	v_mfma_f32_16x16x32_bf16 v[32:35], v[32:35], v[88:91], v[36:39]
	s_nop 4
	v_mul_f32_e32 v56, v65, v65
	v_mul_f32_e32 v57, v67, v67
	v_fmac_f32_e32 v56, v64, v64
	v_fmac_f32_e32 v57, v66, v66
	v_add_f32_e32 v52, v56, v57
	v_mul_f32_e32 v36, v33, v33
	v_mul_f32_e32 v37, v35, v35
	v_add_f32_e32 v52, v60, v52
	v_fmac_f32_e32 v36, v32, v32
	v_fmac_f32_e32 v37, v34, v34
	v_add_f32_e32 v40, v52, v40
	v_add_f32_e32 v36, v36, v37
	v_add_f32_e32 v36, v40, v36
	ds_bpermute_b32 v37, v140, v36
	s_waitcnt lgkmcnt(0)
	v_add_f32_e32 v36, v36, v37
	ds_bpermute_b32 v37, v141, v36
	s_and_saveexec_b64 s[14:15], s[8:9]
	s_cbranch_execz .LBB0_95
	s_waitcnt lgkmcnt(0)
	v_add_f32_e32 v36, v36, v37
	ds_write_b32 v142, v36
	s_branch .LBB0_95
.Lp3_last:
	s_waitcnt vmcnt(0)
	s_branch .LBB0_98

; #define MFMA16(a, b, c) __builtin_amdgcn_mfma_f32_16x16x32_bf16(a, b, c, 0, 0, 0)
; __device__ __forceinline__ unsigned cvt2(float lo, float hi) { bf16v2_t r = __builtin_convertvector((f32x2){lo, hi}, bf16v2_t); return __builtin_bit_cast(unsigned, r); }
; __device__ __forceinline__ void hgrn_pass1_all(LAS unsigned char* lds, const unsigned char* R, bf16_t* ST, float* DBUF, const float* lbp, int u0, int ustep, int tid) {
;     ...
;     for (int unit = u0; unit < 2048; unit += ustep) {
;         const int bh = unit >> 7, n = unit & 127, b = bh >> 2, h = bh & 3;
;         float lf[16]; u32x4 vw[2];
; #pragma unroll
;         for (int i = 0; i < 16; ++i) lf[i] = zn[i];
;         vw[0] = vwn[0]; vw[1] = vwn[1];
;     ...
;         store_vt(vt, vw, tid);
;         __syncthreads();
;         bf16x8 bV[2];
; #pragma unroll
;         for (int ks = 0; ks < 2; ++ks) bV[ks] = LDFRAG(vt, 16 * w + fr, KT_STRIDE, 32 * ks + 8 * fq);
;         bf16_t* up = ST + (size_t)unit * 16384 + (size_t)(16 * w + fr) * 128 + 4 * fq;
; #pragma unroll
;         for (int kt = 0; kt < 8; ++kt) { f32x4 acc = (f32x4){0.f, 0.f, 0.f, 0.f};
; #pragma unroll
;             for (int ks = 0; ks < 2; ++ks) acc = MFMA16(LDFRAG(kdt, 16 * kt + fr, KT_STRIDE, 32 * ks + 8 * fq), bV[ks], acc);
;             u32x2 o; o.x = cvt2(acc[0], acc[1]); o.y = cvt2(acc[2], acc[3]);
;             *(u32x2*)(up + 16 * kt) = o; }
.LBB0_127:
	s_or_b64 exec, exec, s[10:11]
	ds_write_b16 v66, v20 offset:18432
	ds_write_b16_d16_hi v66, v20 offset:18576
	ds_write_b16 v66, v21 offset:18720
	ds_write_b16_d16_hi v66, v21 offset:18864
	ds_write_b16 v66, v22 offset:19008
	ds_write_b16_d16_hi v66, v22 offset:19152
	ds_write_b16 v66, v23 offset:19296
	ds_write_b16_d16_hi v66, v23 offset:19440
	ds_write_b16 v67, v16 offset:18432
	ds_write_b16_d16_hi v67, v16 offset:18576
	ds_write_b16 v67, v17 offset:18720
	ds_write_b16_d16_hi v67, v17 offset:18864
	ds_write_b16 v67, v18 offset:19008
	ds_write_b16_d16_hi v67, v18 offset:19152
	ds_write_b16 v67, v19 offset:19296
	ds_write_b16_d16_hi v67, v19 offset:19440
	s_waitcnt lgkmcnt(0)
	s_barrier
	ds_read_b128 v[20:23], v68 offset:18432
	ds_read_b128 v[16:19], v68 offset:18496
	ds_read_b128 v[38:41], v69
	ds_read_b128 v[42:45], v69 offset:64
	s_waitcnt lgkmcnt(1)
	v_mfma_f32_16x16x32_bf16 v[38:41], v[38:41], v[20:23], 0
	v_readlane_b32 s10, v254, 63
	v_readlane_b32 s11, v252, 0
	s_andn2_b64 vcc, exec, s[24:25]
	s_waitcnt lgkmcnt(0)
	v_mfma_f32_16x16x32_bf16 v[38:41], v[42:45], v[16:19], v[38:41]
	ds_read_b128 v[42:45], v69 offset:2368
	v_lshl_add_u64 v[32:33], v[32:33], 0, s[10:11]
	v_readlane_b32 s10, v254, 47
	v_readlane_b32 s11, v254, 48
	s_nop 3
	v_cvt_pk_bf16_f32 v38, v38, v39
	v_cvt_pk_bf16_f32 v39, v40, v41
	global_store_dwordx2 v[34:35], v[38:39], off
	ds_read_b128 v[38:41], v69 offset:2304
	s_waitcnt lgkmcnt(0)
	v_mfma_f32_16x16x32_bf16 v[38:41], v[38:41], v[20:23], 0
	s_waitcnt vmcnt(1)
	v_mov_b32_e32 v46, v78
	v_mov_b32_e32 v47, v79
	v_mov_b32_e32 v48, v80
	v_mfma_f32_16x16x32_bf16 v[38:41], v[42:45], v[16:19], v[38:41]
	ds_read_b128 v[42:45], v69 offset:4672
	v_mov_b32_e32 v49, v81
	v_mov_b32_e32 v50, v82
	v_mov_b32_e32 v51, v83
	v_mov_b32_e32 v52, v84
	s_nop 2
	v_cvt_pk_bf16_f32 v38, v38, v39
	v_cvt_pk_bf16_f32 v39, v40, v41
	global_store_dwordx2 v[34:35], v[38:39], off offset:32
	ds_read_b128 v[38:41], v69 offset:4608
	s_waitcnt lgkmcnt(0)
	v_mfma_f32_16x16x32_bf16 v[38:41], v[38:41], v[20:23], 0
	v_mov_b32_e32 v53, v85
	s_mov_b32 s14, s41
	v_mfma_f32_16x16x32_bf16 v[38:41], v[42:45], v[16:19], v[38:41]
	ds_read_b128 v[42:45], v69 offset:6976
	s_nop 6
	v_cvt_pk_bf16_f32 v38, v38, v39
	v_cvt_pk_bf16_f32 v39, v40, v41
	global_store_dwordx2 v[34:35], v[38:39], off offset:64
	ds_read_b128 v[38:41], v69 offset:6912
	s_waitcnt lgkmcnt(0)
	v_mfma_f32_16x16x32_bf16 v[38:41], v[38:41], v[20:23], 0
	v_mfma_f32_16x16x32_bf16 v[38:41], v[42:45], v[16:19], v[38:41]
	ds_read_b128 v[42:45], v69 offset:9280
	s_nop 6
	v_cvt_pk_bf16_f32 v38, v38, v39
	v_cvt_pk_bf16_f32 v39, v40, v41
	global_store_dwordx2 v[34:35], v[38:39], off offset:96
	ds_read_b128 v[38:41], v69 offset:9216
	s_waitcnt lgkmcnt(0)
	v_mfma_f32_16x16x32_bf16 v[38:41], v[38:41], v[20:23], 0
	v_mfma_f32_16x16x32_bf16 v[38:41], v[42:45], v[16:19], v[38:41]
	ds_read_b128 v[42:45], v69 offset:11584
	s_nop 6
	v_cvt_pk_bf16_f32 v38, v38, v39
	v_cvt_pk_bf16_f32 v39, v40, v41
	global_store_dwordx2 v[34:35], v[38:39], off offset:128
	ds_read_b128 v[38:41], v69 offset:11520
	s_waitcnt lgkmcnt(0)
	v_mfma_f32_16x16x32_bf16 v[38:41], v[38:41], v[20:23], 0
	v_mfma_f32_16x16x32_bf16 v[38:41], v[42:45], v[16:19], v[38:41]
	ds_read_b128 v[42:45], v69 offset:13888
	s_nop 6
	v_cvt_pk_bf16_f32 v38, v38, v39
	v_cvt_pk_bf16_f32 v39, v40, v41
	global_store_dwordx2 v[34:35], v[38:39], off offset:160
	ds_read_b128 v[38:41], v69 offset:13824
	s_waitcnt lgkmcnt(0)
	v_mfma_f32_16x16x32_bf16 v[38:41], v[38:41], v[20:23], 0
	v_mfma_f32_16x16x32_bf16 v[38:41], v[42:45], v[16:19], v[38:41]
	v_mov_b32_e32 v42, v74
	v_mov_b32_e32 v43, v75
	v_mov_b32_e32 v44, v76
	v_mov_b32_e32 v45, v77
	s_nop 3
	v_cvt_pk_bf16_f32 v38, v38, v39
	v_cvt_pk_bf16_f32 v39, v40, v41
	global_store_dwordx2 v[34:35], v[38:39], off offset:192
	ds_read_b128 v[38:41], v69 offset:16128
	s_waitcnt lgkmcnt(0)
	v_mfma_f32_16x16x32_bf16 v[20:23], v[38:41], v[20:23], 0
	ds_read_b128 v[38:41], v69 offset:16192
	s_waitcnt lgkmcnt(0)
	v_mfma_f32_16x16x32_bf16 v[16:19], v[38:41], v[16:19], v[20:23]
	s_nop 4
	v_mov_b64_e32 v[22:23], v[10:11]
	v_mov_b32_e32 v38, v70
	v_mov_b32_e32 v39, v71
	v_cvt_pk_bf16_f32 v16, v16, v17
	v_cvt_pk_bf16_f32 v17, v18, v19
	global_store_dwordx2 v[34:35], v[16:17], off offset:224
	v_lshl_add_u64 v[34:35], v[34:35], 0, s[10:11]
	v_readlane_b32 s10, v254, 34
	v_mov_b64_e32 v[18:19], v[14:15]
	s_add_i32 s40, s40, s10
	v_mov_b32_e32 v40, v72
	v_mov_b32_e32 v41, v73
	v_mov_b64_e32 v[20:21], v[8:9]
	v_mov_b64_e32 v[16:17], v[12:13]
	s_cbranch_vccz .LBB0_142
; #define HG_LOADZ(dst, LFp, r0_) do { const float* lfp_ = (LFp) + (size_t)((r0_) + seg * 16) * AW + h * 128 + k; \
;     _Pragma("unroll") for (int i = 0; i < 16; ++i) (dst)[i] = lfp_[(size_t)i * AW]; } while (0)
; __device__ __forceinline__ void hgrn_pass1_all(LAS unsigned char* lds, const unsigned char* R, bf16_t* ST, float* DBUF, const float* lbp, int u0, int ustep, int tid) {
;     ...
;     for (int unit = u0; unit < 2048; unit += ustep) {
;         const int bh = unit >> 7, n = unit & 127, b = bh >> 2, h = bh & 3;
;         float lf[16]; u32x4 vw[2];
; #pragma unroll
;         for (int i = 0; i < 16; ++i) lf[i] = zn[i];
;         vw[0] = vwn[0]; vw[1] = vwn[1];
;         __syncthreads();
;         { const int un = unit + ustep; if (un < 2048) { const int bh2 = un >> 7, n2 = un & 127, b2 = bh2 >> 2, h2 = bh2 & 3; const size_t r2 = (size_t)b2 * SEQ + n2 * 64;
;             { const int h = h2; HG_LOADZ(zn, LF, r2); } load_v(vwn, V + r2 * AW + h2 * 128, tid); } }
;         HG_CUMSUM(tot)
.LBB0_128:
	s_and_b32 vcc_lo, s14, 0x180
	v_or_b32_e32 v54, vcc_lo, v2
	v_lshlrev_b32_e32 v54, 2, v54
	global_load_dword v54, v54, s[2:3]
	s_add_i32 s41, s14, s74
	s_cmpk_gt_i32 s41, 0x7ff
	s_cselect_b64 s[24:25], -1, 0
	s_and_b64 vcc, exec, s[24:25]
	s_barrier
	s_cbranch_vccnz .Lp1_last
	s_ashr_i32 s10, s41, 9
	s_ashr_i32 s11, s10, 31
	s_lshl_b64 s[10:11], s[10:11], 13
	s_and_b32 s16, s40, 0x1fc0
	s_or_b32 s10, s10, s16
	v_lshl_add_u64 v[8:9], s[10:11], 0, v[26:27]
	s_and_b32 s15, s41, 0x180
	v_lshlrev_b64 v[8:9], 11, v[8:9]
	v_lshl_add_u64 v[8:9], s[12:13], 0, v[8:9]
	s_lshl_b32 s36, s15, 2
	v_lshl_add_u64 v[8:9], v[8:9], 0, s[36:37]
	v_lshl_add_u64 v[8:9], v[8:9], 0, v[0:1]
	s_movk_i32 s16, 0x1000
	v_add_co_u32_e32 v10, vcc, s16, v8
	s_movk_i32 s16, 0x2000
	s_nop 0
	v_addc_co_u32_e32 v11, vcc, 0, v9, vcc
	v_add_co_u32_e32 v12, vcc, s16, v8
	s_movk_i32 s16, 0x3000
	s_nop 0
	v_addc_co_u32_e32 v13, vcc, 0, v9, vcc
	global_load_dword v70, v[8:9], off
	global_load_dword v71, v[8:9], off offset:2048
	global_load_dword v72, v[12:13], off offset:-4096
	global_load_dword v73, v[10:11], off offset:2048
	global_load_dword v74, v[12:13], off
	global_load_dword v75, v[12:13], off offset:2048
	v_add_co_u32_e32 v10, vcc, s16, v8
	s_movk_i32 s16, 0x4000
	s_nop 0
	v_addc_co_u32_e32 v11, vcc, 0, v9, vcc
	v_add_co_u32_e32 v12, vcc, s16, v8
	s_movk_i32 s16, 0x5000
	s_nop 0
	v_addc_co_u32_e32 v13, vcc, 0, v9, vcc
	global_load_dword v76, v[12:13], off offset:-4096
	global_load_dword v77, v[10:11], off offset:2048
	global_load_dword v78, v[12:13], off
	global_load_dword v79, v[12:13], off offset:2048
	v_add_co_u32_e32 v10, vcc, s16, v8
	s_lshl_b64 s[10:11], s[10:11], 10
	s_nop 0
	v_addc_co_u32_e32 v11, vcc, 0, v9, vcc
	s_movk_i32 s16, 0x6000
	s_add_u32 s10, s23, s10
	v_add_co_u32_e32 v12, vcc, s16, v8
	s_addc_u32 s11, s35, s11
	s_lshl_b32 s15, s15, 1
	v_addc_co_u32_e32 v13, vcc, 0, v9, vcc
	s_movk_i32 s16, 0x7000
	s_add_u32 s10, s10, s15
	v_add_co_u32_e32 v8, vcc, s16, v8
	s_addc_u32 s11, s11, 0
	v_mov_b32_e32 v37, v1
	global_load_dword v80, v[12:13], off offset:-4096
	global_load_dword v81, v[10:11], off offset:2048
	global_load_dword v82, v[12:13], off
	global_load_dword v83, v[12:13], off offset:2048
	v_addc_co_u32_e32 v9, vcc, 0, v9, vcc
	v_lshl_add_u64 v[12:13], s[10:11], 0, v[36:37]
	global_load_dword v84, v[8:9], off
	global_load_dword v85, v[8:9], off offset:2048
	v_lshl_add_u64 v[8:9], v[28:29], 1, v[12:13]
	v_lshl_add_u64 v[12:13], v[30:31], 1, v[12:13]
	global_load_dwordx4 v[8:11], v[8:9], off
	s_nop 0
	global_load_dwordx4 v[12:15], v[12:13], off
.LBB0_130:
	s_and_b32 s10, s14, 0x180
	v_mul_f32_e32 v37, 0xbfb8aa3b, v38
	v_exp_f32_e32 v37, v37
	s_mov_b32 s14, 0x800000
	v_mul_f32_e32 v39, 0xbfb8aa3b, v39
	v_exp_f32_e32 v39, v39
	v_add_f32_e32 v37, 1.0, v37
	v_rcp_f32_e32 v37, v37
	s_mov_b32 s15, 0x3f317217
	v_add_f32_e32 v39, 1.0, v39
	v_rcp_f32_e32 v39, v39
	s_mov_b32 s16, 0x7f800000
	v_mul_f32_e32 v40, 0xbfb8aa3b, v40
	v_exp_f32_e32 v40, v40
	v_mul_f32_e32 v41, 0xbfb8aa3b, v41
	v_exp_f32_e32 v41, v41
	v_mul_f32_e32 v42, 0xbfb8aa3b, v42
	v_add_f32_e32 v40, 1.0, v40
	v_rcp_f32_e32 v40, v40
	v_add_f32_e32 v41, 1.0, v41
	v_rcp_f32_e32 v41, v41
	v_exp_f32_e32 v42, v42
	v_mul_f32_e32 v43, 0xbfb8aa3b, v43
	v_exp_f32_e32 v43, v43
	v_mul_f32_e32 v44, 0xbfb8aa3b, v44
	v_add_f32_e32 v42, 1.0, v42
	v_rcp_f32_e32 v42, v42
	v_add_f32_e32 v43, 1.0, v43
	v_rcp_f32_e32 v43, v43
	v_exp_f32_e32 v44, v44
	v_mul_f32_e32 v45, 0xbfb8aa3b, v45
	v_exp_f32_e32 v45, v45
	v_mul_f32_e32 v46, 0xbfb8aa3b, v46
	v_add_f32_e32 v44, 1.0, v44
	v_rcp_f32_e32 v44, v44
	v_add_f32_e32 v45, 1.0, v45
	v_rcp_f32_e32 v45, v45
	v_exp_f32_e32 v46, v46
	v_mul_f32_e32 v47, 0xbfb8aa3b, v47
	v_exp_f32_e32 v47, v47
	v_mul_f32_e32 v48, 0xbfb8aa3b, v48
	v_add_f32_e32 v46, 1.0, v46
	v_rcp_f32_e32 v46, v46
	v_add_f32_e32 v47, 1.0, v47
	v_rcp_f32_e32 v47, v47
	v_exp_f32_e32 v48, v48
	v_mul_f32_e32 v49, 0xbfb8aa3b, v49
	v_exp_f32_e32 v49, v49
	v_mul_f32_e32 v50, 0xbfb8aa3b, v50
	v_add_f32_e32 v48, 1.0, v48
	v_rcp_f32_e32 v48, v48
	v_add_f32_e32 v49, 1.0, v49
	v_rcp_f32_e32 v49, v49
	v_exp_f32_e32 v50, v50
	v_mul_f32_e32 v51, 0xbfb8aa3b, v51
	v_exp_f32_e32 v51, v51
	v_mul_f32_e32 v52, 0xbfb8aa3b, v52
	v_add_f32_e32 v50, 1.0, v50
	v_rcp_f32_e32 v50, v50
	v_add_f32_e32 v51, 1.0, v51
	v_rcp_f32_e32 v51, v51
	v_exp_f32_e32 v52, v52
	v_mul_f32_e32 v53, 0xbfb8aa3b, v53
	v_exp_f32_e32 v53, v53
	v_add_f32_e32 v52, 1.0, v52
	v_rcp_f32_e32 v52, v52
	v_add_f32_e32 v53, 1.0, v53
	v_rcp_f32_e32 v53, v53
	s_waitcnt vmcnt(18)
	v_sub_f32_e32 v55, 1.0, v54
	v_fma_f32 v37, v37, v55, v54
	v_max_f32_e32 v38, 0x1e3ce508, v37
	v_cmp_gt_f32_e32 vcc, s14, v38
	v_fma_f32 v39, v39, v55, v54
	v_max_f32_e32 v39, 0x1e3ce508, v39
	v_cndmask_b32_e64 v37, 0, 32, vcc
	v_ldexp_f32 v37, v38, v37
	v_log_f32_e32 v37, v37
	v_fma_f32 v40, v40, v55, v54
	v_max_f32_e32 v40, 0x1e3ce508, v40
	v_fma_f32 v41, v41, v55, v54
	v_mul_f32_e32 v56, 0x3f317217, v37
	v_fma_f32 v56, v37, s15, -v56
	v_fmac_f32_e32 v56, 0x3377d1cf, v37
	v_fmac_f32_e32 v56, 0x3f317217, v37
	v_cmp_lt_f32_e64 s[10:11], |v37|, s16
	v_max_f32_e32 v41, 0x1e3ce508, v41
	v_fma_f32 v42, v42, v55, v54
	v_cndmask_b32_e64 v37, v37, v56, s[10:11]
	v_cndmask_b32_e32 v56, 0, v209, vcc
	v_cmp_gt_f32_e32 vcc, s14, v39
	v_sub_f32_e32 v37, v37, v56
	v_max_f32_e32 v42, 0x1e3ce508, v42
	v_cndmask_b32_e64 v56, 0, 32, vcc
	v_ldexp_f32 v56, v39, v56
	v_log_f32_e32 v56, v56
	v_fma_f32 v43, v43, v55, v54
	v_max_f32_e32 v43, 0x1e3ce508, v43
	v_fma_f32 v44, v44, v55, v54
	v_mul_f32_e32 v57, 0x3f317217, v56
	v_fma_f32 v57, v56, s15, -v57
	v_fmac_f32_e32 v57, 0x3377d1cf, v56
	v_fmac_f32_e32 v57, 0x3f317217, v56
	v_cmp_lt_f32_e64 s[10:11], |v56|, s16
	v_max_f32_e32 v44, 0x1e3ce508, v44
	v_fma_f32 v45, v45, v55, v54
	v_cndmask_b32_e64 v56, v56, v57, s[10:11]
	v_cndmask_b32_e32 v57, 0, v209, vcc
	v_cmp_gt_f32_e32 vcc, s14, v40
	v_sub_f32_e32 v56, v56, v57
	v_max_f32_e32 v45, 0x1e3ce508, v45
	v_cndmask_b32_e64 v57, 0, 32, vcc
	v_ldexp_f32 v57, v40, v57
	v_log_f32_e32 v57, v57
	v_fma_f32 v46, v46, v55, v54
	v_max_f32_e32 v46, 0x1e3ce508, v46
	v_fma_f32 v47, v47, v55, v54
	v_mul_f32_e32 v58, 0x3f317217, v57
	v_fma_f32 v58, v57, s15, -v58
	v_fmac_f32_e32 v58, 0x3377d1cf, v57
	v_fmac_f32_e32 v58, 0x3f317217, v57
	v_cmp_lt_f32_e64 s[10:11], |v57|, s16
	v_max_f32_e32 v47, 0x1e3ce508, v47
	v_fma_f32 v48, v48, v55, v54
	v_cndmask_b32_e64 v57, v57, v58, s[10:11]
	v_cndmask_b32_e32 v58, 0, v209, vcc
	v_cmp_gt_f32_e32 vcc, s14, v41
	v_sub_f32_e32 v57, v57, v58
	v_max_f32_e32 v48, 0x1e3ce508, v48
	v_cndmask_b32_e64 v58, 0, 32, vcc
	v_ldexp_f32 v58, v41, v58
	v_log_f32_e32 v58, v58
	v_fma_f32 v49, v49, v55, v54
	v_max_f32_e32 v49, 0x1e3ce508, v49
	v_fma_f32 v50, v50, v55, v54
	v_mul_f32_e32 v59, 0x3f317217, v58
	v_fma_f32 v59, v58, s15, -v59
	v_fmac_f32_e32 v59, 0x3377d1cf, v58
	v_fmac_f32_e32 v59, 0x3f317217, v58
	v_cmp_lt_f32_e64 s[10:11], |v58|, s16
	v_max_f32_e32 v50, 0x1e3ce508, v50
	v_fma_f32 v51, v51, v55, v54
	v_cndmask_b32_e64 v58, v58, v59, s[10:11]
	v_cndmask_b32_e32 v59, 0, v209, vcc
	v_cmp_gt_f32_e32 vcc, s14, v42
	v_sub_f32_e32 v58, v58, v59
	v_max_f32_e32 v51, 0x1e3ce508, v51
	v_cndmask_b32_e64 v59, 0, 32, vcc
	v_ldexp_f32 v59, v42, v59
	v_log_f32_e32 v59, v59
	v_fma_f32 v52, v52, v55, v54
	v_max_f32_e32 v52, 0x1e3ce508, v52
	v_fmac_f32_e32 v54, v53, v55
	v_mul_f32_e32 v60, 0x3f317217, v59
	v_fma_f32 v60, v59, s15, -v60
	v_fmac_f32_e32 v60, 0x3377d1cf, v59
	v_fmac_f32_e32 v60, 0x3f317217, v59
	v_cmp_lt_f32_e64 s[10:11], |v59|, s16
	v_max_f32_e32 v53, 0x1e3ce508, v54
	s_nop 0
	v_cndmask_b32_e64 v59, v59, v60, s[10:11]
	v_cndmask_b32_e32 v60, 0, v209, vcc
	v_cmp_gt_f32_e32 vcc, s14, v43
	v_sub_f32_e32 v59, v59, v60
	s_nop 0
	v_cndmask_b32_e64 v60, 0, 32, vcc
	v_ldexp_f32 v60, v43, v60
	v_log_f32_e32 v60, v60
	s_nop 0
	v_mul_f32_e32 v61, 0x3f317217, v60
	v_fma_f32 v61, v60, s15, -v61
	v_fmac_f32_e32 v61, 0x3377d1cf, v60
	v_fmac_f32_e32 v61, 0x3f317217, v60
	v_cmp_lt_f32_e64 s[10:11], |v60|, s16
	s_nop 1
	v_cndmask_b32_e64 v60, v60, v61, s[10:11]
	v_cndmask_b32_e32 v61, 0, v209, vcc
	v_cmp_gt_f32_e32 vcc, s14, v44
	v_sub_f32_e32 v60, v60, v61
	s_nop 0
	v_cndmask_b32_e64 v61, 0, 32, vcc
	v_ldexp_f32 v61, v44, v61
	v_log_f32_e32 v61, v61
	s_nop 0
	v_mul_f32_e32 v86, 0x3f317217, v61
	v_fma_f32 v86, v61, s15, -v86
	v_fmac_f32_e32 v86, 0x3377d1cf, v61
	v_fmac_f32_e32 v86, 0x3f317217, v61
	v_cmp_lt_f32_e64 s[10:11], |v61|, s16
	s_nop 1
	v_cndmask_b32_e64 v61, v61, v86, s[10:11]
	v_cndmask_b32_e32 v86, 0, v209, vcc
	v_cmp_gt_f32_e32 vcc, s14, v45
	v_sub_f32_e32 v61, v61, v86
	s_nop 0
	v_cndmask_b32_e64 v86, 0, 32, vcc
	v_ldexp_f32 v86, v45, v86
	v_log_f32_e32 v86, v86
	s_nop 0
	v_mul_f32_e32 v87, 0x3f317217, v86
	v_fma_f32 v87, v86, s15, -v87
	v_fmac_f32_e32 v87, 0x3377d1cf, v86
	v_fmac_f32_e32 v87, 0x3f317217, v86
	v_cmp_lt_f32_e64 s[10:11], |v86|, s16
	s_nop 1
	v_cndmask_b32_e64 v86, v86, v87, s[10:11]
	v_cndmask_b32_e32 v87, 0, v209, vcc
	v_cmp_gt_f32_e32 vcc, s14, v46
	v_sub_f32_e32 v86, v86, v87
	s_nop 0
	v_cndmask_b32_e64 v87, 0, 32, vcc
	v_ldexp_f32 v87, v46, v87
	v_log_f32_e32 v87, v87
	s_nop 0
	v_mul_f32_e32 v88, 0x3f317217, v87
	v_fma_f32 v88, v87, s15, -v88
	v_fmac_f32_e32 v88, 0x3377d1cf, v87
	v_fmac_f32_e32 v88, 0x3f317217, v87
	v_cmp_lt_f32_e64 s[10:11], |v87|, s16
	s_nop 1
	v_cndmask_b32_e64 v87, v87, v88, s[10:11]
	v_cndmask_b32_e32 v88, 0, v209, vcc
	v_cmp_gt_f32_e32 vcc, s14, v47
	v_sub_f32_e32 v87, v87, v88
	s_nop 0
	v_cndmask_b32_e64 v88, 0, 32, vcc
	v_ldexp_f32 v88, v47, v88
	v_log_f32_e32 v88, v88
	s_nop 0
	v_mul_f32_e32 v89, 0x3f317217, v88
	v_fma_f32 v89, v88, s15, -v89
	v_fmac_f32_e32 v89, 0x3377d1cf, v88
	v_fmac_f32_e32 v89, 0x3f317217, v88
	v_cmp_lt_f32_e64 s[10:11], |v88|, s16
	s_nop 1
	v_cndmask_b32_e64 v88, v88, v89, s[10:11]
	v_cndmask_b32_e32 v89, 0, v209, vcc
	v_cmp_gt_f32_e32 vcc, s14, v48
	v_sub_f32_e32 v94, v88, v89
	s_nop 0
	v_cndmask_b32_e64 v88, 0, 32, vcc
	v_ldexp_f32 v88, v48, v88
	v_log_f32_e32 v88, v88
	s_nop 0
	v_mul_f32_e32 v89, 0x3f317217, v88
	v_fma_f32 v89, v88, s15, -v89
	v_fmac_f32_e32 v89, 0x3377d1cf, v88
	v_fmac_f32_e32 v89, 0x3f317217, v88
	v_cmp_lt_f32_e64 s[10:11], |v88|, s16
	s_nop 1
	v_cndmask_b32_e64 v88, v88, v89, s[10:11]
	v_cndmask_b32_e32 v89, 0, v209, vcc
	v_cmp_gt_f32_e32 vcc, s14, v49
	v_sub_f32_e32 v95, v88, v89
	s_nop 0
	v_cndmask_b32_e64 v88, 0, 32, vcc
	v_ldexp_f32 v88, v49, v88
	v_log_f32_e32 v88, v88
	s_nop 0
	v_mul_f32_e32 v89, 0x3f317217, v88
	v_fma_f32 v89, v88, s15, -v89
	v_fmac_f32_e32 v89, 0x3377d1cf, v88
	v_fmac_f32_e32 v89, 0x3f317217, v88
	v_cmp_lt_f32_e64 s[10:11], |v88|, s16
	s_nop 1
	v_cndmask_b32_e64 v88, v88, v89, s[10:11]
	v_cndmask_b32_e32 v89, 0, v209, vcc
	v_cmp_gt_f32_e32 vcc, s14, v50
	v_sub_f32_e32 v96, v88, v89
	s_nop 0
	v_cndmask_b32_e64 v88, 0, 32, vcc
	v_ldexp_f32 v88, v50, v88
	v_log_f32_e32 v88, v88
	s_nop 0
	v_mul_f32_e32 v89, 0x3f317217, v88
	v_fma_f32 v89, v88, s15, -v89
	v_fmac_f32_e32 v89, 0x3377d1cf, v88
	v_fmac_f32_e32 v89, 0x3f317217, v88
	v_cmp_lt_f32_e64 s[10:11], |v88|, s16
	s_nop 1
	v_cndmask_b32_e64 v88, v88, v89, s[10:11]
	v_cndmask_b32_e32 v89, 0, v209, vcc
	v_cmp_gt_f32_e32 vcc, s14, v51
	v_sub_f32_e32 v97, v88, v89
	s_nop 0
	v_cndmask_b32_e64 v88, 0, 32, vcc
	v_ldexp_f32 v88, v51, v88
	v_log_f32_e32 v88, v88
	s_nop 0
	v_mul_f32_e32 v89, 0x3f317217, v88
	v_fma_f32 v89, v88, s15, -v89
	v_fmac_f32_e32 v89, 0x3377d1cf, v88
	v_fmac_f32_e32 v89, 0x3f317217, v88
	v_cmp_lt_f32_e64 s[10:11], |v88|, s16
	s_nop 1
	v_cndmask_b32_e64 v88, v88, v89, s[10:11]
	v_cndmask_b32_e32 v89, 0, v209, vcc
	v_cmp_gt_f32_e32 vcc, s14, v52
	v_sub_f32_e32 v98, v88, v89
	s_nop 0
	v_cndmask_b32_e64 v88, 0, 32, vcc
	v_ldexp_f32 v88, v52, v88
	v_log_f32_e32 v88, v88
	s_nop 0
	v_mul_f32_e32 v89, 0x3f317217, v88
	v_fma_f32 v89, v88, s15, -v89
	v_fmac_f32_e32 v89, 0x3377d1cf, v88
	v_fmac_f32_e32 v89, 0x3f317217, v88
	v_cmp_lt_f32_e64 s[10:11], |v88|, s16
	s_nop 1
	v_cndmask_b32_e64 v88, v88, v89, s[10:11]
	v_cndmask_b32_e32 v89, 0, v209, vcc
	v_cmp_gt_f32_e32 vcc, s14, v53
	v_sub_f32_e32 v99, v88, v89
	s_nop 0
	v_cndmask_b32_e64 v54, 0, 32, vcc
	v_ldexp_f32 v54, v53, v54
	v_log_f32_e32 v54, v54
	s_nop 0
	v_mul_f32_e32 v55, 0x3f317217, v54
	v_fma_f32 v55, v54, s15, -v55
	v_fmac_f32_e32 v55, 0x3377d1cf, v54
	v_fmac_f32_e32 v55, 0x3f317217, v54
	v_cmp_lt_f32_e64 s[10:11], |v54|, s16
	s_nop 1
	v_cndmask_b32_e64 v54, v54, v55, s[10:11]
	v_cndmask_b32_e32 v55, 0, v209, vcc
	v_sub_f32_e32 v55, v54, v55
	v_add_f32_e32 v54, 0, v37
	v_add_f32_e32 v88, v56, v54
	v_add_f32_e32 v89, v57, v88
	v_add_f32_e32 v90, v58, v89
	v_add_f32_e32 v91, v59, v90
	v_add_f32_e32 v92, v60, v91
	v_add_f32_e32 v93, v61, v92
	v_add_f32_e32 v86, v86, v93
	v_add_f32_e32 v87, v87, v86
	v_add_f32_e32 v94, v94, v87
	v_add_f32_e32 v95, v95, v94
	v_add_f32_e32 v96, v96, v95
	v_add_f32_e32 v97, v97, v96
	v_add_f32_e32 v98, v98, v97
	v_add_f32_e32 v37, v99, v98
	v_add_f32_e32 v55, v55, v37
	ds_write_b32 v25, v55 offset:36864
	s_waitcnt lgkmcnt(0)
	s_barrier
	ds_read2st64_b32 v[56:57], v64 offset0:144 offset1:146
	ds_read2st64_b32 v[60:61], v64 offset0:148 offset1:150
	v_mov_b32_e32 v59, 0
	s_and_saveexec_b64 s[10:11], s[8:9]
	s_cbranch_execz .LBB0_138
	v_cmp_lt_i32_e32 vcc, 1, v63
	s_mov_b64 s[14:15], 0
	s_and_saveexec_b64 s[16:17], vcc
	s_xor_b64 s[28:29], exec, s[16:17]
	s_cbranch_execz .LBB0_140
	v_cmp_eq_u32_e32 vcc, 2, v63
	s_mov_b64 s[14:15], -1
	s_and_saveexec_b64 s[30:31], vcc
	s_cbranch_execz .LBB0_134
	s_waitcnt lgkmcnt(1)
	v_add_f32_e32 v59, v56, v57
	s_xor_b64 s[14:15], exec, -1
